# stack v79 + lru_item sqrtf expansions: the zero/infinity class select after the corrected root removed (argument never infinite; for +0 the corrected root is already +0; bit-identical)
# speedup vs baseline: 1.0061x; 1.0007x over previous
; #define LAS __attribute__((address_space(3)))
; __device__ __forceinline__ bf16_t f2bf(float f) { return (bf16_t)(pk2(f, 0.f) & 0xffffu); }
; __device__ __forceinline__ float bf2f(unsigned b) { return __uint_as_float(b << 16); }
; __device__ __forceinline__ f32x4 mfma16(bf16x8 a, bf16x8 b, f32x4 c) { return __builtin_amdgcn_mfma_f32_16x16x32_bf16(a, b, c, 0, 0, 0); }
; __device__ __forceinline__ void lds_barrier() { asm volatile("s_waitcnt lgkmcnt(0)" ::: "memory"); __builtin_amdgcn_s_barrier(); asm volatile("" ::: "memory"); }
; __device__ __forceinline__ void lru_item(const Params& p, int l, int item, LAS unsigned char* lds) {
;     ...
; #pragma unroll
;     for (int i = 0; i < 19; ++i) { const int t = t0 - 3 + i; xr[i] = (t >= 0) ? (unsigned)p.z[(Tb + (t >= 0 ? t : 0)) * ZLD + 2304 + ch] : 0u; }
;     bf16x8 wa0[4], wa1[4], wx0[4], wx1[4];
;     { const bf16_t* wap = p.waT + (((size_t)l * 4 + h) * 64 + fr) * 64 + fq * 8; const bf16_t* wxp = p.wxT + (((size_t)l * 4 + h) * 64 + fr) * 64 + fq * 8;
; #pragma unroll
;       for (int jt = 0; jt < 4; ++jt) { wa0[jt] = *(const bf16x8*)(wap + jt * 1024); wa1[jt] = *(const bf16x8*)(wap + jt * 1024 + 32); wx0[jt] = *(const bf16x8*)(wxp + jt * 1024); wx1[jt] = *(const bf16x8*)(wxp + jt * 1024 + 32); } }
;     { const float cb = p.conv_b[l * 256 + ch], cw0 = p.conv_w[(l * 4 + 0) * 256 + ch], cw1 = p.conv_w[(l * 4 + 1) * 256 + ch], cw2 = p.conv_w[(l * 4 + 2) * 256 + ch], cw3 = p.conv_w[(l * 4 + 3) * 256 + ch];
; #pragma unroll
;       for (int i = 0; i < 16; ++i) { const float xc = cb + bf2f(xr[i]) * cw0 + bf2f(xr[i + 1]) * cw1 + bf2f(xr[i + 2]) * cw2 + bf2f(xr[i + 3]) * cw3; xa[i * 72 + lane] = f2bf(xc); xf[i * 66 + lane] = xc; } }
;     lds_barrier();
;     { const bf16x8 a0 = *(const LAS bf16x8*)(xa + fr * 72 + fq * 8), a1 = *(const LAS bf16x8*)(xa + fr * 72 + 32 + fq * 8);
; #pragma unroll
;       for (int jt = 0; jt < 4; ++jt) {
;           f32x4 pa = mfma16(a0, wa0[jt], ZERO4); pa = mfma16(a1, wa1[jt], pa);
;           f32x4 px = mfma16(a0, wx0[jt], ZERO4); px = mfma16(a1, wx1[jt], px);
;           const int cj = l * 256 + h * 64 + jt * 16 + fr; const float bav = p.ba[cj], bxv = p.bx[cj], sp = p.spl[cj];
.LBB0_393:
	s_or_b64 exec, exec, s[74:75]
	s_movk_i32 s4, 0x2a00
	v_and_b32_e32 v91, 15, v1
	s_or_b32 s98, s16, s40
	v_or_b32_e32 v148, s98, v91
	v_ashrrev_i32_e32 v149, 31, v148
	v_lshlrev_b64 v[148:149], 2, v[148:149]
	v_lshl_add_u64 v[150:151], s[30:31], 0, v[148:149]
	v_lshl_add_u64 v[152:153], s[6:7], 0, v[148:149]
	v_lshl_add_u64 v[154:155], s[34:35], 0, v[148:149]
	global_load_dword v156, v[150:151], off
	global_load_dword v157, v[152:153], off
	global_load_dword v158, v[154:155], off
	global_load_dword v159, v[150:151], off offset:64
	global_load_dword v160, v[152:153], off offset:64
	global_load_dword v161, v[154:155], off offset:64
	global_load_dword v162, v[150:151], off offset:128
	global_load_dword v163, v[152:153], off offset:128
	global_load_dword v164, v[154:155], off offset:128
	global_load_dword v165, v[150:151], off offset:192
	global_load_dword v166, v[152:153], off offset:192
	global_load_dword v167, v[154:155], off offset:192
	v_mul_lo_u32 v4, v0, s4
	s_or_b32 s4, s12, s16
	v_add_u32_e32 v79, 0, v4
	v_or_b32_e32 v4, s4, v91
	v_mov_b32_e32 v5, s13
	v_lshlrev_b64 v[4:5], 7, v[4:5]
	v_lshl_add_u64 v[6:7], s[70:71], 0, v[4:5]
	v_and_b32_e32 v20, 48, v3
	v_mov_b32_e32 v21, v2
	v_lshl_add_u64 v[6:7], v[6:7], 0, v[20:21]
	v_lshl_add_u64 v[4:5], s[36:37], 0, v[4:5]
	v_add_co_u32_e32 v8, vcc, s80, v6
	v_lshl_add_u64 v[4:5], v[4:5], 0, v[20:21]
	s_nop 0
	v_addc_co_u32_e32 v9, vcc, 0, v7, vcc
	v_or_b32_e32 v100, s40, v78
	v_mov_b32_e32 v98, s17
	v_mov_b32_e32 v99, s22
	v_add_co_u32_e32 v16, vcc, s80, v4
	v_ashrrev_i32_e32 v101, 31, v100
	s_nop 0
	v_addc_co_u32_e32 v17, vcc, 0, v5, vcc
	v_lshl_add_u64 v[98:99], v[100:101], 2, v[98:99]
	global_load_dwordx4 v[60:63], v[6:7], off
	global_load_dwordx4 v[64:67], v[6:7], off offset:64
	global_load_dwordx4 v[68:71], v[4:5], off
	global_load_dwordx4 v[72:75], v[4:5], off offset:64
	global_load_dwordx4 v[44:47], v[6:7], off offset:2048
	global_load_dwordx4 v[48:51], v[6:7], off offset:2112
	global_load_dwordx4 v[52:55], v[4:5], off offset:2048
	global_load_dwordx4 v[56:59], v[4:5], off offset:2112
	global_load_dwordx4 v[28:31], v[8:9], off
	global_load_dwordx4 v[32:35], v[8:9], off offset:64
	global_load_dwordx4 v[36:39], v[16:17], off
	global_load_dwordx4 v[40:43], v[16:17], off offset:64
	s_nop 0
	global_load_dwordx4 v[4:7], v[8:9], off offset:2048
	s_nop 0
	global_load_dwordx4 v[8:11], v[8:9], off offset:2112
	s_nop 0
	global_load_dwordx4 v[12:15], v[16:17], off offset:2048
	s_nop 0
	global_load_dwordx4 v[16:19], v[16:17], off offset:2112
	v_mov_b32_e32 v96, s33
	global_load_dword v21, v[98:99], off
	v_or_b32_e32 v98, s87, v78
	v_mov_b32_e32 v97, s44
	v_ashrrev_i32_e32 v99, 31, v98
	v_lshl_add_u64 v[96:97], v[98:99], 2, v[96:97]
	global_load_dword v98, v[96:97], off
	global_load_dword v99, v[96:97], off offset:1024
	global_load_dword v100, v[96:97], off offset:2048
	s_nop 0
	global_load_dword v96, v[96:97], off offset:3072
	v_lshlrev_b32_e32 v78, 1, v3
	v_add_u32_e32 v97, v79, v78
	v_add_u32_e32 v80, v97, v78
	s_or_b32 s4, s16, s40
	s_mov_b32 s16, 0xf800000
	v_lshrrev_b32_e32 v92, 4, v3
	v_lshl_add_u32 v1, v1, 3, 0
	v_add_u32_e32 v1, 0x15000, v1
	s_waitcnt vmcnt(3)
	v_lshlrev_b32_e32 v88, 16, v88
	v_lshlrev_b32_e32 v87, 16, v87
	v_lshlrev_b32_e32 v85, 16, v85
	v_lshlrev_b32_e32 v83, 16, v83
	v_lshlrev_b32_e32 v26, 16, v26
	v_lshlrev_b32_e32 v22, 16, v22
	v_lshlrev_b32_e32 v24, 16, v24
	v_lshlrev_b32_e32 v23, 16, v23
	v_lshlrev_b32_e32 v27, 16, v27
	v_lshlrev_b32_e32 v25, 16, v25
	v_lshlrev_b32_e32 v82, 16, v82
	v_lshlrev_b32_e32 v81, 16, v81
	v_lshlrev_b32_e32 v86, 16, v86
	v_lshlrev_b32_e32 v84, 16, v84
	v_lshlrev_b32_e32 v90, 16, v90
	v_lshlrev_b32_e32 v89, 16, v89
	v_lshlrev_b32_e32 v94, 16, v94
	v_lshlrev_b32_e32 v93, 16, v93
	v_lshlrev_b32_e32 v95, 16, v95
	v_cmp_lt_i32_e32 vcc, 2, v76
	s_nop 1
	v_cndmask_b32_e32 v88, 0, v88, vcc
	v_cmp_lt_i32_e32 vcc, 1, v76
	s_nop 1
	v_cndmask_b32_e32 v87, 0, v87, vcc
	v_cmp_lt_i32_e32 vcc, 0, v76
	s_nop 1
	v_cndmask_b32_e32 v85, 0, v85, vcc
	v_fma_f32 v88, v88, v98, v21
	s_waitcnt vmcnt(2)
	v_fmac_f32_e32 v88, v87, v99
	v_fma_f32 v87, v87, v98, v21
	s_waitcnt vmcnt(1)
	v_fmac_f32_e32 v88, v85, v100
	v_fmac_f32_e32 v87, v85, v99
	s_waitcnt vmcnt(0)
	v_fmac_f32_e32 v88, v83, v96
	v_cvt_pk_bf16_f32 v101, v88, v2
	v_fmac_f32_e32 v87, v83, v100
	v_fma_f32 v85, v85, v98, v21
	ds_write_b16 v97, v101
	v_fmac_f32_e32 v87, v26, v96
	v_cvt_pk_bf16_f32 v101, v87, v2
	v_fmac_f32_e32 v85, v83, v99
	v_fma_f32 v83, v83, v98, v21
	ds_write_b16 v97, v101 offset:144
	v_add_u32_e32 v101, 0x800, v80
	v_fmac_f32_e32 v85, v26, v100
	v_fmac_f32_e32 v83, v26, v99
	ds_write2_b32 v101, v88, v87 offset0:64 offset1:130
	v_fmac_f32_e32 v85, v22, v96
	v_cvt_pk_bf16_f32 v87, v85, v2
	v_fmac_f32_e32 v83, v22, v100
	v_fma_f32 v26, v26, v98, v21
	ds_write_b16 v97, v87 offset:288
	v_fmac_f32_e32 v83, v24, v96
	v_cvt_pk_bf16_f32 v87, v83, v2
	v_fmac_f32_e32 v26, v22, v99
	v_fma_f32 v22, v22, v98, v21
	ds_write_b16 v97, v87 offset:432
	v_add_u32_e32 v87, 0xa00, v80
	v_fmac_f32_e32 v26, v24, v100
	v_fmac_f32_e32 v22, v24, v99
	ds_write2_b32 v87, v85, v83 offset0:68 offset1:134
	v_fmac_f32_e32 v26, v23, v96
	v_cvt_pk_bf16_f32 v83, v26, v2
	v_fmac_f32_e32 v22, v23, v100
	ds_write_b16 v97, v83 offset:576
	v_fmac_f32_e32 v22, v27, v96
	v_cvt_pk_bf16_f32 v83, v22, v2
	ds_write_b16 v97, v83 offset:720
	v_add_u32_e32 v83, 0xc00, v80
	ds_write2_b32 v83, v26, v22 offset0:72 offset1:138
	v_fma_f32 v22, v24, v98, v21
	v_fmac_f32_e32 v22, v23, v99
	v_fma_f32 v23, v23, v98, v21
	v_fmac_f32_e32 v22, v27, v100
	v_fmac_f32_e32 v23, v27, v99
	v_fmac_f32_e32 v22, v25, v96
	v_cvt_pk_bf16_f32 v24, v22, v2
; #define LAS __attribute__((address_space(3)))
; __device__ __forceinline__ float fexp(float x) { return __builtin_amdgcn_exp2f(x * LOG2E); }
; __device__ __forceinline__ float sigm(float x) { return frcp(1.f + fexp(-x)); }
; __device__ __forceinline__ f32x4 mfma16(bf16x8 a, bf16x8 b, f32x4 c) { return __builtin_amdgcn_mfma_f32_16x16x32_bf16(a, b, c, 0, 0, 0); }
; __device__ __forceinline__ void lds_barrier() { asm volatile("s_waitcnt lgkmcnt(0)" ::: "memory"); __builtin_amdgcn_s_barrier(); asm volatile("" ::: "memory"); }
; __device__ __forceinline__ void lru_item(const Params& p, int l, int item, LAS unsigned char* lds) {
;     ...
;     lds_barrier();
;     { const bf16x8 a0 = *(const LAS bf16x8*)(xa + fr * 72 + fq * 8), a1 = *(const LAS bf16x8*)(xa + fr * 72 + 32 + fq * 8);
; #pragma unroll
;       for (int jt = 0; jt < 4; ++jt) {
;           f32x4 pa = mfma16(a0, wa0[jt], ZERO4); pa = mfma16(a1, wa1[jt], pa);
;           f32x4 px = mfma16(a0, wx0[jt], ZERO4); px = mfma16(a1, wx1[jt], px);
;           const int cj = l * 256 + h * 64 + jt * 16 + fr; const float bav = p.ba[cj], bxv = p.bx[cj], sp = p.spl[cj];
; #pragma unroll
;           for (int jj = 0; jj < 4; ++jj) { const int t = fq * 4 + jj; const float r = sigm(pa[jj] + bav), ig = sigm(px[jj] + bxv); const float la = -8.f * r * sp;
;               const float a = fexp(la); float mult = sqrtf(fmaxf(1.f - fexp(2.f * la), 0.f)); if (t0 + t == 0) mult = 1.f;
;               const int li = t * 66 + jt * 16 + fr; const float xcv = xf[li]; sa[li] = a; xf[li] = mult * ig * xcv; }
	v_fmac_f32_e32 v23, v25, v100
	ds_write_b16 v97, v24 offset:864
	v_fmac_f32_e32 v23, v82, v96
	v_cvt_pk_bf16_f32 v24, v23, v2
	ds_write_b16 v97, v24 offset:1008
	v_add_u32_e32 v24, 0xe00, v80
	ds_write2_b32 v24, v22, v23 offset0:76 offset1:142
	v_fma_f32 v22, v27, v98, v21
	v_fmac_f32_e32 v22, v25, v99
	v_fmac_f32_e32 v22, v82, v100
	v_fmac_f32_e32 v22, v81, v96
	v_cvt_pk_bf16_f32 v23, v22, v2
	ds_write_b16 v97, v23 offset:1152
	v_fma_f32 v23, v25, v98, v21
	v_fmac_f32_e32 v23, v82, v99
	v_fmac_f32_e32 v23, v81, v100
	v_fmac_f32_e32 v23, v86, v96
	v_cvt_pk_bf16_f32 v24, v23, v2
	ds_write_b16 v97, v24 offset:1296
	v_add_u32_e32 v24, 0x1000, v80
	ds_write2_b32 v24, v22, v23 offset0:80 offset1:146
	v_fma_f32 v22, v82, v98, v21
	v_fmac_f32_e32 v22, v81, v99
	v_fmac_f32_e32 v22, v86, v100
	v_fmac_f32_e32 v22, v84, v96
	v_cvt_pk_bf16_f32 v23, v22, v2
	ds_write_b16 v97, v23 offset:1440
	v_fma_f32 v23, v81, v98, v21
	v_fmac_f32_e32 v23, v86, v99
	v_fmac_f32_e32 v23, v84, v100
	v_fmac_f32_e32 v23, v90, v96
	v_cvt_pk_bf16_f32 v24, v23, v2
	ds_write_b16 v97, v24 offset:1584
	v_add_u32_e32 v24, 0x1200, v80
	ds_write2_b32 v24, v22, v23 offset0:84 offset1:150
	v_fma_f32 v22, v86, v98, v21
	v_fmac_f32_e32 v22, v84, v99
	v_fmac_f32_e32 v22, v90, v100
	v_fmac_f32_e32 v22, v89, v96
	v_cvt_pk_bf16_f32 v23, v22, v2
	ds_write_b16 v97, v23 offset:1728
	v_fma_f32 v23, v84, v98, v21
	v_fmac_f32_e32 v23, v90, v99
	v_fmac_f32_e32 v23, v89, v100
	v_fmac_f32_e32 v23, v94, v96
	v_cvt_pk_bf16_f32 v24, v23, v2
	ds_write_b16 v97, v24 offset:1872
	v_add_u32_e32 v24, 0x1400, v80
	ds_write2_b32 v24, v22, v23 offset0:88 offset1:154
	v_fma_f32 v22, v90, v98, v21
	v_fmac_f32_e32 v22, v89, v99
	v_fmac_f32_e32 v21, v89, v98
	v_fmac_f32_e32 v22, v94, v100
	v_fmac_f32_e32 v21, v94, v99
	v_fmac_f32_e32 v22, v93, v96
	v_cvt_pk_bf16_f32 v23, v22, v2
	v_fmac_f32_e32 v21, v93, v100
	ds_write_b16 v97, v23 offset:2016
	v_fmac_f32_e32 v21, v95, v96
	v_cvt_pk_bf16_f32 v23, v21, v2
	ds_write_b16 v97, v23 offset:2160
	v_add_u32_e32 v23, 0x1600, v80
	ds_write2_b32 v23, v22, v21 offset0:92 offset1:158
	v_mul_u32_u24_e32 v21, 0x90, v91
	s_waitcnt lgkmcnt(0)
	s_barrier
	v_add3_u32 v24, v79, v21, v20
	ds_read_b128 v[20:23], v24
	ds_read_b128 v[24:27], v24 offset:64
	s_waitcnt lgkmcnt(1)
	v_mfma_f32_16x16x32_bf16 v[60:63], v[20:23], v[60:63], 0
	v_or_b32_e32 v86, s4, v91
	v_ashrrev_i32_e32 v87, 31, v86
	s_waitcnt lgkmcnt(0)
	v_mfma_f32_16x16x32_bf16 v[82:85], v[24:27], v[64:67], v[60:63]
	v_mfma_f32_16x16x32_bf16 v[60:63], v[20:23], v[68:71], 0
	v_mfma_f32_16x16x32_bf16 v[70:73], v[24:27], v[72:75], v[60:63]
	v_mfma_f32_16x16x32_bf16 v[44:47], v[20:23], v[44:47], 0
	s_nop 5
	v_lshlrev_b64 v[60:61], 2, v[86:87]
	v_lshl_add_u64 v[64:65], s[30:31], 0, v[60:61]
	v_lshl_add_u64 v[62:63], s[6:7], 0, v[60:61]
	v_lshl_add_u64 v[60:61], s[34:35], 0, v[60:61]
	v_mfma_f32_16x16x32_bf16 v[48:51], v[24:27], v[48:51], v[44:47]
	s_waitcnt vmcnt(0)
	v_mov_b32_e32 v81, v156
	v_mov_b32_e32 v86, v157
	v_mov_b32_e32 v87, v158
	v_add_f32_e32 v66, v82, v81
	v_mul_f32_e32 v66, 0xbfb8aa3b, v66
	v_exp_f32_e32 v66, v66
	s_waitcnt vmcnt(1)
	v_add_f32_e32 v67, v70, v86
	v_mul_f32_e32 v67, 0xbfb8aa3b, v67
	v_exp_f32_e32 v67, v67
	v_add_f32_e32 v66, 1.0, v66
	v_rcp_f32_e32 v66, v66
	v_mfma_f32_16x16x32_bf16 v[44:47], v[20:23], v[52:55], 0
	v_add_f32_e32 v67, 1.0, v67
	v_rcp_f32_e32 v68, v67
	v_mul_f32_e32 v66, 0xc1000000, v66
	s_waitcnt vmcnt(0)
	v_mul_f32_e32 v66, v87, v66
	v_mul_f32_e32 v67, 0x3fb8aa3b, v66
	v_add_f32_e32 v66, v66, v66
	v_mul_f32_e32 v66, 0x3fb8aa3b, v66
	v_exp_f32_e32 v66, v66
	v_exp_f32_e32 v69, v67
	v_mfma_f32_16x16x32_bf16 v[44:47], v[24:27], v[56:59], v[44:47]
	v_sub_f32_e32 v66, 1.0, v66
	v_max_f32_e32 v66, 0, v66
	v_mfma_f32_16x16x32_bf16 v[28:31], v[20:23], v[28:31], 0
	v_sqrt_f32_e32 v67, v66
	v_mfma_f32_16x16x32_bf16 v[32:35], v[24:27], v[32:35], v[28:31]
	v_add_u32_e32 v70, -1, v67
	v_fma_f32 v74, -v70, v67, v66
	v_cmp_ge_f32_e64 s[4:5], 0, v74
	v_add_u32_e32 v74, 1, v67
	v_mfma_f32_16x16x32_bf16 v[28:31], v[20:23], v[36:39], 0
	v_cndmask_b32_e64 v70, v67, v70, s[4:5]
	v_fma_f32 v67, -v74, v67, v66
	v_cmp_lt_f32_e64 s[4:5], 0, v67
	v_mfma_f32_16x16x32_bf16 v[28:31], v[24:27], v[40:43], v[28:31]
	s_nop 0
	v_cndmask_b32_e64 v67, v70, v74, s[4:5]
	s_movk_i32 s4, 0x108
	v_mfma_f32_16x16x32_bf16 v[4:7], v[20:23], v[4:7], 0
	v_mov_b32_e32 v66, v67
	v_or_b32_e32 v67, v76, v92
	v_cmp_eq_u32_e32 vcc, 0, v67
	v_mfma_f32_16x16x32_bf16 v[8:11], v[24:27], v[8:11], v[4:7]
	s_nop 0
	v_cndmask_b32_e64 v70, v66, 1.0, vcc
	v_mad_u32_u24 v66, v92, s4, v91
	v_lshl_add_u32 v74, v66, 2, v79
	v_add_u32_e32 v75, 0x800, v74
	ds_read2_b32 v[66:67], v75 offset0:64 offset1:80
	v_mul_f32_e32 v68, v68, v70
	ds_write_b32 v74, v69 offset:6528
	v_mfma_f32_16x16x32_bf16 v[4:7], v[20:23], v[12:15], 0
	s_waitcnt lgkmcnt(1)
	v_mul_f32_e32 v66, v66, v68
	ds_write_b32 v74, v66 offset:2304
	v_add_f32_e32 v66, v83, v81
	v_mul_f32_e32 v66, 0xbfb8aa3b, v66
	v_exp_f32_e32 v66, v66
	v_add_f32_e32 v68, v71, v86
	v_mul_f32_e32 v68, 0xbfb8aa3b, v68
	v_exp_f32_e32 v68, v68
	v_add_f32_e32 v66, 1.0, v66
	v_rcp_f32_e32 v66, v66
	v_mfma_f32_16x16x32_bf16 v[4:7], v[24:27], v[16:19], v[4:7]
	v_add_f32_e32 v68, 1.0, v68
	v_rcp_f32_e32 v70, v68
	v_mul_f32_e32 v66, 0xc1000000, v66
	v_mul_f32_e32 v66, v87, v66
	v_mul_f32_e32 v68, 0x3fb8aa3b, v66
	v_add_f32_e32 v66, v66, v66
	v_mul_f32_e32 v66, 0x3fb8aa3b, v66
	v_exp_f32_e32 v66, v66
	v_exp_f32_e32 v71, v68
	v_sub_f32_e32 v66, 1.0, v66
	v_max_f32_e32 v66, 0, v66
	s_nop 0
	v_sqrt_f32_e32 v68, v66
	s_nop 0
	v_add_u32_e32 v69, -1, v68
	v_fma_f32 v76, -v69, v68, v66
	v_cmp_ge_f32_e64 s[6:7], 0, v76
	v_add_u32_e32 v76, 1, v68
	s_nop 0
	v_cndmask_b32_e64 v69, v68, v69, s[6:7]
	v_fma_f32 v68, -v76, v68, v66
	v_cmp_lt_f32_e64 s[6:7], 0, v68
	s_nop 1
	v_cndmask_b32_e64 v68, v69, v76, s[6:7]
	s_nop 1
	v_mov_b32_e32 v66, v68
	ds_read2_b32 v[68:69], v75 offset0:130 offset1:146
	v_mul_f32_e32 v66, v70, v66
	ds_write_b32 v74, v71 offset:6792
	s_waitcnt lgkmcnt(1)
; __device__ __forceinline__ float fexp(float x) { return __builtin_amdgcn_exp2f(x * LOG2E); }
; __device__ __forceinline__ float sigm(float x) { return frcp(1.f + fexp(-x)); }
; __device__ __forceinline__ void lru_item(const Params& p, int l, int item, LAS unsigned char* lds) {
;     ...
;           const int cj = l * 256 + h * 64 + jt * 16 + fr; const float bav = p.ba[cj], bxv = p.bx[cj], sp = p.spl[cj];
; #pragma unroll
;           for (int jj = 0; jj < 4; ++jj) { const int t = fq * 4 + jj; const float r = sigm(pa[jj] + bav), ig = sigm(px[jj] + bxv); const float la = -8.f * r * sp;
;               const float a = fexp(la); float mult = sqrtf(fmaxf(1.f - fexp(2.f * la), 0.f)); if (t0 + t == 0) mult = 1.f;
;               const int li = t * 66 + jt * 16 + fr; const float xcv = xf[li]; sa[li] = a; xf[li] = mult * ig * xcv; }
	v_mul_f32_e32 v66, v68, v66
	ds_write_b32 v74, v66 offset:2568
	v_add_f32_e32 v66, v84, v81
	v_mul_f32_e32 v66, 0xbfb8aa3b, v66
	v_exp_f32_e32 v66, v66
	v_add_f32_e32 v68, v72, v86
	v_mul_f32_e32 v68, 0xbfb8aa3b, v68
	v_exp_f32_e32 v68, v68
	v_add_f32_e32 v66, 1.0, v66
	v_rcp_f32_e32 v66, v66
	v_add_f32_e32 v68, 1.0, v68
	v_rcp_f32_e32 v68, v68
	v_mul_f32_e32 v66, 0xc1000000, v66
	v_mul_f32_e32 v66, v87, v66
	v_mul_f32_e32 v70, 0x3fb8aa3b, v66
	v_add_f32_e32 v66, v66, v66
	v_mul_f32_e32 v66, 0x3fb8aa3b, v66
	v_exp_f32_e32 v66, v66
	v_exp_f32_e32 v72, v70
	v_sub_f32_e32 v66, 1.0, v66
	v_max_f32_e32 v66, 0, v66
	s_nop 0
	v_sqrt_f32_e32 v70, v66
	s_nop 0
	v_add_u32_e32 v71, -1, v70
	v_fma_f32 v76, -v71, v70, v66
	v_cmp_ge_f32_e64 s[6:7], 0, v76
	v_add_u32_e32 v76, 1, v70
	s_nop 0
	v_cndmask_b32_e64 v71, v70, v71, s[6:7]
	v_fma_f32 v70, -v76, v70, v66
	v_cmp_lt_f32_e64 s[6:7], 0, v70
	s_nop 1
	v_cndmask_b32_e64 v70, v71, v76, s[6:7]
	s_nop 1
	v_mov_b32_e32 v66, v70
	ds_read2_b32 v[70:71], v75 offset0:196 offset1:212
	v_mul_f32_e32 v66, v68, v66
	v_add_f32_e32 v68, v73, v86
	v_mul_f32_e32 v68, 0xbfb8aa3b, v68
	v_exp_f32_e32 v68, v68
	s_waitcnt lgkmcnt(0)
	v_mul_f32_e32 v66, v70, v66
	ds_write_b32 v74, v66 offset:2832
	v_add_f32_e32 v66, v85, v81
	v_mul_f32_e32 v66, 0xbfb8aa3b, v66
	v_exp_f32_e32 v66, v66
	v_add_f32_e32 v68, 1.0, v68
	v_rcp_f32_e32 v70, v68
	ds_write_b32 v74, v72 offset:7056
	v_add_f32_e32 v66, 1.0, v66
	v_rcp_f32_e32 v66, v66
	s_nop 0
	v_mul_f32_e32 v66, 0xc1000000, v66
	v_mul_f32_e32 v66, v87, v66
	v_mul_f32_e32 v68, 0x3fb8aa3b, v66
	v_add_f32_e32 v66, v66, v66
	v_mul_f32_e32 v66, 0x3fb8aa3b, v66
	v_exp_f32_e32 v66, v66
	v_exp_f32_e32 v68, v68
	v_sub_f32_e32 v66, 1.0, v66
	v_max_f32_e32 v66, 0, v66
	s_nop 0
	v_sqrt_f32_e32 v72, v66
	s_nop 0
	v_add_u32_e32 v73, -1, v72
	v_fma_f32 v76, -v73, v72, v66
	v_cmp_ge_f32_e64 s[6:7], 0, v76
	v_add_u32_e32 v76, 1, v72
	s_nop 0
	v_cndmask_b32_e64 v73, v72, v73, s[6:7]
	v_fma_f32 v72, -v76, v72, v66
	v_cmp_lt_f32_e64 s[6:7], 0, v72
	s_nop 1
	v_cndmask_b32_e64 v72, v73, v76, s[6:7]
	s_nop 1
	v_mov_b32_e32 v76, v72
	v_add_u32_e32 v66, 0xc00, v74
	ds_read2_b32 v[72:73], v66 offset0:6 offset1:22
	v_mov_b32_e32 v52, v159
	v_mov_b32_e32 v53, v160
	v_mov_b32_e32 v54, v161
	v_mul_f32_e32 v70, v70, v76
	s_waitcnt lgkmcnt(0)
	v_mul_f32_e32 v70, v72, v70
	s_waitcnt vmcnt(2)
	v_add_f32_e32 v48, v48, v52
	v_mul_f32_e32 v48, 0xbfb8aa3b, v48
	v_exp_f32_e32 v48, v48
	s_waitcnt vmcnt(1)
	v_add_f32_e32 v44, v44, v53
	v_mul_f32_e32 v44, 0xbfb8aa3b, v44
	v_exp_f32_e32 v44, v44
	v_add_f32_e32 v48, 1.0, v48
	v_rcp_f32_e32 v48, v48
	v_add_f32_e32 v45, v45, v53
	v_add_f32_e32 v44, 1.0, v44
	v_rcp_f32_e32 v44, v44
	v_mul_f32_e32 v48, 0xc1000000, v48
	s_waitcnt vmcnt(0)
	v_mul_f32_e32 v48, v54, v48
	v_mul_f32_e32 v55, 0x3fb8aa3b, v48
	v_add_f32_e32 v48, v48, v48
	v_mul_f32_e32 v48, 0x3fb8aa3b, v48
	v_exp_f32_e32 v48, v48
	v_exp_f32_e32 v55, v55
	v_mul_f32_e32 v45, 0xbfb8aa3b, v45
	v_exp_f32_e32 v45, v45
	v_sub_f32_e32 v48, 1.0, v48
	v_max_f32_e32 v48, 0, v48
	ds_write_b32 v74, v55 offset:6592
	v_sqrt_f32_e32 v56, v48
	v_add_f32_e32 v45, 1.0, v45
	v_rcp_f32_e32 v45, v45
	v_add_u32_e32 v57, -1, v56
	v_fma_f32 v58, -v57, v56, v48
	v_cmp_ge_f32_e64 s[6:7], 0, v58
	v_add_u32_e32 v58, 1, v56
	s_nop 0
	v_cndmask_b32_e64 v57, v56, v57, s[6:7]
	v_fma_f32 v56, -v58, v56, v48
	v_cmp_lt_f32_e64 s[6:7], 0, v56
	s_nop 1
	v_cndmask_b32_e64 v56, v57, v58, s[6:7]
	s_nop 1
	v_mov_b32_e32 v48, v56
	v_cndmask_b32_e64 v48, v48, 1.0, vcc
	v_mul_f32_e32 v44, v44, v48
	v_mul_f32_e32 v48, v67, v44
	v_add_f32_e32 v44, v49, v52
	v_mul_f32_e32 v44, 0xbfb8aa3b, v44
	v_exp_f32_e32 v44, v44
	s_nop 0
	v_add_f32_e32 v44, 1.0, v44
	v_rcp_f32_e32 v44, v44
	s_nop 0
	v_mul_f32_e32 v44, 0xc1000000, v44
	v_mul_f32_e32 v44, v54, v44
	v_mul_f32_e32 v49, 0x3fb8aa3b, v44
	v_add_f32_e32 v44, v44, v44
	v_mul_f32_e32 v44, 0x3fb8aa3b, v44
	v_exp_f32_e32 v44, v44
	v_exp_f32_e32 v49, v49
	v_sub_f32_e32 v44, 1.0, v44
	v_max_f32_e32 v44, 0, v44
	ds_write_b32 v74, v49 offset:6856
	v_sqrt_f32_e32 v55, v44
	s_nop 0
	v_add_u32_e32 v56, -1, v55
	v_fma_f32 v57, -v56, v55, v44
	v_cmp_ge_f32_e64 s[6:7], 0, v57
	v_add_u32_e32 v57, 1, v55
	s_nop 0
	v_cndmask_b32_e64 v56, v55, v56, s[6:7]
	v_fma_f32 v55, -v57, v55, v44
	v_cmp_lt_f32_e64 s[6:7], 0, v55
	s_nop 1
	v_cndmask_b32_e64 v55, v56, v57, s[6:7]
	s_nop 1
	v_mov_b32_e32 v44, v55
	v_mul_f32_e32 v44, v45, v44
	v_mul_f32_e32 v44, v69, v44
	ds_write_b32 v74, v44 offset:2632
	v_add_f32_e32 v44, v50, v52
	v_mul_f32_e32 v44, 0xbfb8aa3b, v44
	v_exp_f32_e32 v44, v44
	v_add_f32_e32 v45, v46, v53
	v_mul_f32_e32 v45, 0xbfb8aa3b, v45
	v_exp_f32_e32 v45, v45
	v_add_f32_e32 v44, 1.0, v44
	v_rcp_f32_e32 v44, v44
	v_add_f32_e32 v45, 1.0, v45
	v_rcp_f32_e32 v45, v45
	v_mul_f32_e32 v44, 0xc1000000, v44
	v_mul_f32_e32 v44, v54, v44
	v_mul_f32_e32 v46, 0x3fb8aa3b, v44
	v_add_f32_e32 v44, v44, v44
	v_mul_f32_e32 v44, 0x3fb8aa3b, v44
	v_exp_f32_e32 v44, v44
	v_exp_f32_e32 v46, v46
	v_sub_f32_e32 v44, 1.0, v44
	v_max_f32_e32 v44, 0, v44
	ds_write_b32 v74, v46 offset:7120
	v_sqrt_f32_e32 v49, v44
	s_nop 0
	v_add_u32_e32 v50, -1, v49
	v_fma_f32 v55, -v50, v49, v44
	v_cmp_ge_f32_e64 s[6:7], 0, v55
	v_add_u32_e32 v55, 1, v49
	s_nop 0
	v_cndmask_b32_e64 v50, v49, v50, s[6:7]
	v_fma_f32 v49, -v55, v49, v44
	v_cmp_lt_f32_e64 s[6:7], 0, v49
	s_nop 1
	v_cndmask_b32_e64 v49, v50, v55, s[6:7]
	s_nop 1
	v_mov_b32_e32 v44, v49
	v_mul_f32_e32 v44, v45, v44
	v_mul_f32_e32 v44, v71, v44
	ds_write_b32 v74, v44 offset:2896
	v_add_f32_e32 v44, v51, v52
	v_mul_f32_e32 v44, 0xbfb8aa3b, v44
	v_exp_f32_e32 v44, v44
	v_add_f32_e32 v45, v47, v53
	v_mul_f32_e32 v45, 0xbfb8aa3b, v45
	v_exp_f32_e32 v45, v45
	v_add_f32_e32 v44, 1.0, v44
	v_rcp_f32_e32 v44, v44
	v_add_f32_e32 v45, 1.0, v45
	v_rcp_f32_e32 v45, v45
	v_mul_f32_e32 v44, 0xc1000000, v44
	v_mul_f32_e32 v44, v54, v44
	v_mul_f32_e32 v46, 0x3fb8aa3b, v44
	v_add_f32_e32 v44, v44, v44
	v_mul_f32_e32 v44, 0x3fb8aa3b, v44
	v_exp_f32_e32 v44, v44
	v_exp_f32_e32 v46, v46
	v_sub_f32_e32 v44, 1.0, v44
	v_max_f32_e32 v44, 0, v44
	s_nop 0
	v_sqrt_f32_e32 v47, v44
	s_nop 0
	v_add_u32_e32 v49, -1, v47
	v_fma_f32 v50, -v49, v47, v44
	v_cmp_ge_f32_e64 s[6:7], 0, v50
	v_add_u32_e32 v50, 1, v47
	s_nop 0
	v_cndmask_b32_e64 v49, v47, v49, s[6:7]
	v_fma_f32 v47, -v50, v47, v44
	v_cmp_lt_f32_e64 s[6:7], 0, v47
	s_nop 1
	v_cndmask_b32_e64 v47, v49, v50, s[6:7]
	s_nop 1
	v_mul_f32_e32 v45, v45, v47
	v_add_u32_e32 v44, 0x1c00, v74
	v_mul_f32_e32 v45, v73, v45
	ds_write2_b32 v44, v68, v46 offset0:38 offset1:54
	ds_write2_b32 v66, v70, v45 offset0:6 offset1:22
	v_mov_b32_e32 v40, v162
	v_mov_b32_e32 v41, v163
	v_mov_b32_e32 v42, v164
	s_waitcnt vmcnt(2)
; __device__ __forceinline__ float fexp(float x) { return __builtin_amdgcn_exp2f(x * LOG2E); }
; __device__ __forceinline__ float sigm(float x) { return frcp(1.f + fexp(-x)); }
; __device__ __forceinline__ void lru_item(const Params& p, int l, int item, LAS unsigned char* lds) {
;     ...
;           const int cj = l * 256 + h * 64 + jt * 16 + fr; const float bav = p.ba[cj], bxv = p.bx[cj], sp = p.spl[cj];
; #pragma unroll
;           for (int jj = 0; jj < 4; ++jj) { const int t = fq * 4 + jj; const float r = sigm(pa[jj] + bav), ig = sigm(px[jj] + bxv); const float la = -8.f * r * sp;
;               const float a = fexp(la); float mult = sqrtf(fmaxf(1.f - fexp(2.f * la), 0.f)); if (t0 + t == 0) mult = 1.f;
;               const int li = t * 66 + jt * 16 + fr; const float xcv = xf[li]; sa[li] = a; xf[li] = mult * ig * xcv; }
	v_add_f32_e32 v32, v32, v40
	v_mul_f32_e32 v32, 0xbfb8aa3b, v32
	v_exp_f32_e32 v32, v32
	s_waitcnt vmcnt(1)
	v_add_f32_e32 v28, v28, v41
	v_mul_f32_e32 v28, 0xbfb8aa3b, v28
	v_exp_f32_e32 v28, v28
	v_add_f32_e32 v32, 1.0, v32
	v_rcp_f32_e32 v32, v32
	v_add_f32_e32 v29, v29, v41
	v_add_f32_e32 v28, 1.0, v28
	v_rcp_f32_e32 v28, v28
	v_mul_f32_e32 v32, 0xc1000000, v32
	s_waitcnt vmcnt(0)
	v_mul_f32_e32 v32, v42, v32
	v_mul_f32_e32 v36, 0x3fb8aa3b, v32
	v_add_f32_e32 v32, v32, v32
	v_mul_f32_e32 v32, 0x3fb8aa3b, v32
	v_exp_f32_e32 v32, v32
	v_exp_f32_e32 v36, v36
	v_mul_f32_e32 v29, 0xbfb8aa3b, v29
	v_exp_f32_e32 v29, v29
	v_sub_f32_e32 v32, 1.0, v32
	v_max_f32_e32 v32, 0, v32
	ds_write_b32 v74, v36 offset:6656
	v_sqrt_f32_e32 v37, v32
	v_add_f32_e32 v29, 1.0, v29
	v_rcp_f32_e32 v29, v29
	v_add_u32_e32 v38, -1, v37
	v_fma_f32 v39, -v38, v37, v32
	v_cmp_ge_f32_e64 s[6:7], 0, v39
	v_add_u32_e32 v39, 1, v37
	s_nop 0
	v_cndmask_b32_e64 v38, v37, v38, s[6:7]
	v_fma_f32 v37, -v39, v37, v32
	v_cmp_lt_f32_e64 s[6:7], 0, v37
	s_nop 1
	v_cndmask_b32_e64 v37, v38, v39, s[6:7]
	ds_read2_b32 v[38:39], v75 offset0:96 offset1:112
	s_nop 1
	v_mov_b32_e32 v32, v37
	v_cndmask_b32_e64 v32, v32, 1.0, vcc
	v_mul_f32_e32 v28, v28, v32
	s_waitcnt lgkmcnt(0)
	v_mul_f32_e32 v28, v38, v28
	ds_write2_b32 v75, v48, v28 offset0:80 offset1:96
	v_add_f32_e32 v28, v33, v40
	v_mul_f32_e32 v28, 0xbfb8aa3b, v28
	v_exp_f32_e32 v28, v28
	s_nop 0
	v_add_f32_e32 v28, 1.0, v28
	v_rcp_f32_e32 v28, v28
	s_nop 0
	v_mul_f32_e32 v28, 0xc1000000, v28
	v_mul_f32_e32 v28, v42, v28
	v_mul_f32_e32 v32, 0x3fb8aa3b, v28
	v_add_f32_e32 v28, v28, v28
	v_mul_f32_e32 v28, 0x3fb8aa3b, v28
	v_exp_f32_e32 v28, v28
	v_exp_f32_e32 v32, v32
	v_sub_f32_e32 v28, 1.0, v28
	v_max_f32_e32 v28, 0, v28
	s_nop 0
	v_sqrt_f32_e32 v33, v28
	s_nop 0
	v_add_u32_e32 v36, -1, v33
	v_fma_f32 v37, -v36, v33, v28
	v_cmp_ge_f32_e64 s[6:7], 0, v37
	v_add_u32_e32 v37, 1, v33
	s_nop 0
	v_cndmask_b32_e64 v36, v33, v36, s[6:7]
	v_fma_f32 v33, -v37, v33, v28
	v_cmp_lt_f32_e64 s[6:7], 0, v33
	s_nop 1
	v_cndmask_b32_e64 v33, v36, v37, s[6:7]
	ds_read2_b32 v[36:37], v75 offset0:162 offset1:178
	ds_write_b32 v74, v32 offset:6920
	s_nop 0
	v_mov_b32_e32 v28, v33
	v_mul_f32_e32 v28, v29, v28
	s_waitcnt lgkmcnt(1)
	v_mul_f32_e32 v28, v36, v28
	ds_write_b32 v74, v28 offset:2696
	v_add_f32_e32 v28, v34, v40
	v_mul_f32_e32 v28, 0xbfb8aa3b, v28
	v_exp_f32_e32 v28, v28
	v_add_f32_e32 v29, v30, v41
	v_mul_f32_e32 v29, 0xbfb8aa3b, v29
	v_exp_f32_e32 v29, v29
	v_add_f32_e32 v28, 1.0, v28
	v_rcp_f32_e32 v28, v28
	v_add_f32_e32 v29, 1.0, v29
	v_rcp_f32_e32 v29, v29
	v_mul_f32_e32 v28, 0xc1000000, v28
	v_mul_f32_e32 v28, v42, v28
	v_mul_f32_e32 v30, 0x3fb8aa3b, v28
	v_add_f32_e32 v28, v28, v28
	v_mul_f32_e32 v28, 0x3fb8aa3b, v28
	v_exp_f32_e32 v28, v28
	v_exp_f32_e32 v30, v30
	v_sub_f32_e32 v28, 1.0, v28
	v_max_f32_e32 v28, 0, v28
	s_nop 0
	v_sqrt_f32_e32 v32, v28
	s_nop 0
	v_add_u32_e32 v33, -1, v32
	v_fma_f32 v34, -v33, v32, v28
	v_cmp_ge_f32_e64 s[6:7], 0, v34
	v_add_u32_e32 v34, 1, v32
	s_nop 0
	v_cndmask_b32_e64 v33, v32, v33, s[6:7]
	v_fma_f32 v32, -v34, v32, v28
	v_cmp_lt_f32_e64 s[6:7], 0, v32
	s_nop 1
	v_cndmask_b32_e64 v32, v33, v34, s[6:7]
	s_nop 1
	v_mov_b32_e32 v28, v32
	ds_read2_b32 v[32:33], v75 offset0:228 offset1:244
	v_mul_f32_e32 v28, v29, v28
	v_add_f32_e32 v29, v31, v41
	v_mul_f32_e32 v29, 0xbfb8aa3b, v29
	v_exp_f32_e32 v29, v29
	s_waitcnt lgkmcnt(0)
	v_mul_f32_e32 v28, v32, v28
	ds_write_b32 v74, v28 offset:2960
	v_add_f32_e32 v28, v35, v40
	v_mul_f32_e32 v28, 0xbfb8aa3b, v28
	v_exp_f32_e32 v28, v28
	v_add_f32_e32 v29, 1.0, v29
	v_rcp_f32_e32 v31, v29
	ds_write_b32 v74, v30 offset:7184
	v_add_f32_e32 v28, 1.0, v28
	v_rcp_f32_e32 v28, v28
	s_nop 0
	v_mul_f32_e32 v28, 0xc1000000, v28
	v_mul_f32_e32 v28, v42, v28
	v_mul_f32_e32 v29, 0x3fb8aa3b, v28
	v_add_f32_e32 v28, v28, v28
	v_mul_f32_e32 v28, 0x3fb8aa3b, v28
	v_exp_f32_e32 v28, v28
	v_exp_f32_e32 v30, v29
	v_sub_f32_e32 v28, 1.0, v28
	v_max_f32_e32 v28, 0, v28
	s_nop 0
	v_sqrt_f32_e32 v29, v28
	s_nop 0
	v_add_u32_e32 v32, -1, v29
	v_fma_f32 v34, -v32, v29, v28
	v_cmp_ge_f32_e64 s[6:7], 0, v34
	v_add_u32_e32 v34, 1, v29
	s_nop 0
	v_cndmask_b32_e64 v32, v29, v32, s[6:7]
	v_fma_f32 v29, -v34, v29, v28
	v_cmp_lt_f32_e64 s[6:7], 0, v29
	s_nop 1
	v_cndmask_b32_e64 v29, v32, v34, s[6:7]
	s_nop 1
	v_mov_b32_e32 v32, v29
	ds_read2_b32 v[28:29], v66 offset0:38 offset1:54
	v_mov_b32_e32 v12, v165
	v_mov_b32_e32 v13, v166
	v_mov_b32_e32 v14, v167
	v_mul_f32_e32 v31, v31, v32
	s_waitcnt lgkmcnt(0)
	v_mul_f32_e32 v28, v28, v31
	s_waitcnt vmcnt(2)
	v_add_f32_e32 v8, v8, v12
	v_mul_f32_e32 v8, 0xbfb8aa3b, v8
	v_exp_f32_e32 v8, v8
	s_waitcnt vmcnt(1)
	v_add_f32_e32 v4, v4, v13
	v_mul_f32_e32 v4, 0xbfb8aa3b, v4
	v_exp_f32_e32 v4, v4
	v_add_f32_e32 v8, 1.0, v8
	v_rcp_f32_e32 v8, v8
	v_add_f32_e32 v5, v5, v13
	v_add_f32_e32 v4, 1.0, v4
	v_rcp_f32_e32 v4, v4
	v_mul_f32_e32 v8, 0xc1000000, v8
	s_waitcnt vmcnt(0)
; __device__ __forceinline__ float fexp(float x) { return __builtin_amdgcn_exp2f(x * LOG2E); }
; __device__ __forceinline__ float sigm(float x) { return frcp(1.f + fexp(-x)); }
; __device__ __forceinline__ void lds_barrier() { asm volatile("s_waitcnt lgkmcnt(0)" ::: "memory"); __builtin_amdgcn_s_barrier(); asm volatile("" ::: "memory"); }
; __device__ __forceinline__ void lru_item(const Params& p, int l, int item, LAS unsigned char* lds) {
;     ...
;           const int cj = l * 256 + h * 64 + jt * 16 + fr; const float bav = p.ba[cj], bxv = p.bx[cj], sp = p.spl[cj];
; #pragma unroll
;           for (int jj = 0; jj < 4; ++jj) { const int t = fq * 4 + jj; const float r = sigm(pa[jj] + bav), ig = sigm(px[jj] + bxv); const float la = -8.f * r * sp;
;               const float a = fexp(la); float mult = sqrtf(fmaxf(1.f - fexp(2.f * la), 0.f)); if (t0 + t == 0) mult = 1.f;
;               const int li = t * 66 + jt * 16 + fr; const float xcv = xf[li]; sa[li] = a; xf[li] = mult * ig * xcv; }
;       } }
;     lds_barrier();
	v_mul_f32_e32 v8, v14, v8
	v_mul_f32_e32 v15, 0x3fb8aa3b, v8
	v_add_f32_e32 v8, v8, v8
	v_mul_f32_e32 v8, 0x3fb8aa3b, v8
	v_exp_f32_e32 v8, v8
	v_exp_f32_e32 v15, v15
	v_mul_f32_e32 v5, 0xbfb8aa3b, v5
	v_exp_f32_e32 v5, v5
	v_sub_f32_e32 v8, 1.0, v8
	v_max_f32_e32 v8, 0, v8
	ds_write_b32 v74, v15 offset:6720
	v_sqrt_f32_e32 v16, v8
	v_add_f32_e32 v5, 1.0, v5
	v_rcp_f32_e32 v5, v5
	v_add_u32_e32 v17, -1, v16
	v_fma_f32 v18, -v17, v16, v8
	v_cmp_ge_f32_e64 s[6:7], 0, v18
	v_add_u32_e32 v18, 1, v16
	s_nop 0
	v_cndmask_b32_e64 v17, v16, v17, s[6:7]
	v_fma_f32 v16, -v18, v16, v8
	v_cmp_lt_f32_e64 s[6:7], 0, v16
	s_nop 1
	v_cndmask_b32_e64 v16, v17, v18, s[6:7]
	s_nop 1
	v_mov_b32_e32 v8, v16
	v_cndmask_b32_e64 v8, v8, 1.0, vcc
	v_mul_f32_e32 v4, v4, v8
	v_mul_f32_e32 v4, v39, v4
	ds_write_b32 v74, v4 offset:2496
	v_add_f32_e32 v4, v9, v12
	v_mul_f32_e32 v4, 0xbfb8aa3b, v4
	v_exp_f32_e32 v4, v4
	s_nop 0
	v_add_f32_e32 v4, 1.0, v4
	v_rcp_f32_e32 v4, v4
	s_nop 0
	v_mul_f32_e32 v4, 0xc1000000, v4
	v_mul_f32_e32 v4, v14, v4
	v_mul_f32_e32 v8, 0x3fb8aa3b, v4
	v_add_f32_e32 v4, v4, v4
	v_mul_f32_e32 v4, 0x3fb8aa3b, v4
	v_exp_f32_e32 v4, v4
	v_exp_f32_e32 v8, v8
	v_sub_f32_e32 v4, 1.0, v4
	v_max_f32_e32 v4, 0, v4
	ds_write_b32 v74, v8 offset:6984
	v_sqrt_f32_e32 v9, v4
	s_nop 0
	v_add_u32_e32 v15, -1, v9
	v_fma_f32 v16, -v15, v9, v4
	v_cmp_ge_f32_e64 s[4:5], 0, v16
	v_add_u32_e32 v16, 1, v9
	s_nop 0
	v_cndmask_b32_e64 v15, v9, v15, s[4:5]
	v_fma_f32 v9, -v16, v9, v4
	v_cmp_lt_f32_e64 s[4:5], 0, v9
	s_nop 1
	v_cndmask_b32_e64 v9, v15, v16, s[4:5]
	s_nop 1
	v_mov_b32_e32 v4, v9
	v_mul_f32_e32 v4, v5, v4
	v_mul_f32_e32 v4, v37, v4
	ds_write_b32 v74, v4 offset:2760
	v_add_f32_e32 v4, v10, v12
	v_mul_f32_e32 v4, 0xbfb8aa3b, v4
	v_exp_f32_e32 v4, v4
	v_add_f32_e32 v5, v6, v13
	v_mul_f32_e32 v5, 0xbfb8aa3b, v5
	v_exp_f32_e32 v5, v5
	v_add_f32_e32 v4, 1.0, v4
	v_rcp_f32_e32 v4, v4
	v_add_f32_e32 v5, 1.0, v5
	v_rcp_f32_e32 v5, v5
	v_mul_f32_e32 v4, 0xc1000000, v4
	v_mul_f32_e32 v4, v14, v4
	v_mul_f32_e32 v6, 0x3fb8aa3b, v4
	v_add_f32_e32 v4, v4, v4
	v_mul_f32_e32 v4, 0x3fb8aa3b, v4
	v_exp_f32_e32 v4, v4
	v_exp_f32_e32 v6, v6
	v_sub_f32_e32 v4, 1.0, v4
	v_max_f32_e32 v4, 0, v4
	ds_write_b32 v74, v6 offset:7248
	v_sqrt_f32_e32 v8, v4
	s_nop 0
	v_add_u32_e32 v9, -1, v8
	v_fma_f32 v10, -v9, v8, v4
	v_cmp_ge_f32_e64 s[4:5], 0, v10
	v_add_u32_e32 v10, 1, v8
	s_nop 0
	v_cndmask_b32_e64 v9, v8, v9, s[4:5]
	v_fma_f32 v8, -v10, v8, v4
	v_cmp_lt_f32_e64 s[4:5], 0, v8
	s_nop 1
	v_cndmask_b32_e64 v8, v9, v10, s[4:5]
	s_nop 1
	v_mov_b32_e32 v4, v8
	v_mul_f32_e32 v4, v5, v4
	v_mul_f32_e32 v4, v33, v4
	ds_write_b32 v74, v4 offset:3024
	v_add_f32_e32 v4, v11, v12
	v_mul_f32_e32 v4, 0xbfb8aa3b, v4
	v_exp_f32_e32 v4, v4
	v_add_f32_e32 v5, v7, v13
	v_mul_f32_e32 v5, 0xbfb8aa3b, v5
	v_exp_f32_e32 v5, v5
	v_add_f32_e32 v4, 1.0, v4
	v_rcp_f32_e32 v4, v4
	v_add_f32_e32 v5, 1.0, v5
	v_rcp_f32_e32 v5, v5
	v_mul_f32_e32 v4, 0xc1000000, v4
	v_mul_f32_e32 v4, v14, v4
	v_mul_f32_e32 v6, 0x3fb8aa3b, v4
	v_add_f32_e32 v4, v4, v4
	v_mul_f32_e32 v4, 0x3fb8aa3b, v4
	v_exp_f32_e32 v4, v4
	v_exp_f32_e32 v6, v6
	v_lshl_add_u32 v14, v3, 2, v79
	v_sub_f32_e32 v4, 1.0, v4
	v_max_f32_e32 v4, 0, v4
	ds_write2_b32 v44, v30, v6 offset0:70 offset1:86
	v_sqrt_f32_e32 v7, v4
	s_nop 0
	v_add_u32_e32 v8, -1, v7
	v_fma_f32 v9, -v8, v7, v4
	v_cmp_ge_f32_e64 s[4:5], 0, v9
	v_add_u32_e32 v9, 1, v7
	s_nop 0
	v_cndmask_b32_e64 v8, v7, v8, s[4:5]
	v_fma_f32 v7, -v9, v7, v4
	v_cmp_lt_f32_e64 s[4:5], 0, v7
	s_nop 1
	v_cndmask_b32_e64 v7, v8, v9, s[4:5]
	s_nop 1
	v_mov_b32_e32 v4, v7
	v_mul_f32_e32 v4, v5, v4
	v_mul_f32_e32 v4, v29, v4
	ds_write2_b32 v66, v28, v4 offset0:38 offset1:54
	s_waitcnt lgkmcnt(0)
	s_barrier
; __device__ __forceinline__ void lds_barrier() { asm volatile("s_waitcnt lgkmcnt(0)" ::: "memory"); __builtin_amdgcn_s_barrier(); asm volatile("" ::: "memory"); }
; __device__ __forceinline__ void lru_item(const Params& p, int l, int item, LAS unsigned char* lds) {
;     ...
;     lds_barrier();
;     float Ac[16], Hl[16];
;     { float A = 1.f, H = 0.f;
; #pragma unroll
;       for (int i = 0; i < 16; ++i) { const float a = sa[i * 66 + lane], bt = xf[i * 66 + lane]; H = a * H + bt; A *= a; Ac[i] = A; Hl[i] = H; }
;       ct[(wid * 64 + lane) * 2] = A; ct[(wid * 64 + lane) * 2 + 1] = H; }
;     lds_barrier();
;     { float Ain = 1.f, Hin = 0.f;
;       for (int w = 0; w < wid; ++w) { const float aw = ct[(w * 64 + lane) * 2], hw = ct[(w * 64 + lane) * 2 + 1]; Hin = aw * Hin + hw; Ain *= aw; }
	v_add_u32_e32 v4, 0x1800, v14
	ds_read2_b32 v[22:23], v4 offset0:30 offset1:96
	ds_read_b32 v18, v80 offset:2304
	ds_read2_b32 v[6:7], v4 offset0:162 offset1:228
	v_add_u32_e32 v4, 0x800, v14
	ds_read2_b32 v[20:21], v4 offset0:130 offset1:196
	v_add_u32_e32 v4, 0x1c00, v14
	v_add_u32_e32 v5, 0xc00, v14
	ds_read2_b32 v[8:9], v4 offset0:38 offset1:104
	ds_read2_b32 v[12:13], v5 offset0:6 offset1:72
	s_waitcnt lgkmcnt(4)
	v_fmac_f32_e32 v18, 0, v23
	ds_read2_b32 v[46:47], v4 offset0:170 offset1:236
	ds_read2_b32 v[10:11], v5 offset0:138 offset1:204
	s_waitcnt lgkmcnt(4)
	v_fma_f32 v19, v18, v6, v20
	v_fmac_f32_e32 v21, v19, v7
	s_waitcnt lgkmcnt(2)
	v_fma_f32 v25, v21, v8, v12
	v_fmac_f32_e32 v13, v25, v9
	v_mul_f32_e32 v28, v23, v6
	s_waitcnt lgkmcnt(0)
	v_fma_f32 v17, v13, v46, v10
	v_add_u32_e32 v6, 0x2000, v14
	v_add_u32_e32 v10, 0x1000, v14
	ds_read2_b32 v[40:41], v6 offset0:46 offset1:112
	ds_read2_b32 v[4:5], v10 offset0:14 offset1:80
	ds_read2_b32 v[38:39], v6 offset0:178 offset1:244
	ds_read2_b32 v[42:43], v10 offset0:146 offset1:212
	v_fmac_f32_e32 v11, v17, v47
	v_mov_b32_e32 v6, v7
	v_mov_b32_e32 v26, v8
	s_waitcnt lgkmcnt(2)
	v_fma_f32 v15, v11, v40, v4
	v_fmac_f32_e32 v5, v15, v41
	v_mov_b32_e32 v29, v5
	s_waitcnt lgkmcnt(1)
	v_mov_b32_e32 v7, v38
	v_add_u32_e32 v4, 0x2400, v14
	v_pk_mul_f32 v[32:33], v[28:29], v[6:7]
	s_waitcnt lgkmcnt(0)
	v_mov_b32_e32 v27, v42
	ds_read2_b32 v[48:49], v4 offset0:54 offset1:120
	v_pk_mul_f32 v[36:37], v[32:33], v[26:27]
	v_pk_fma_f32 v[6:7], v[28:29], v[6:7], v[26:27]
	v_mov_b32_e32 v8, v9
	v_mov_b32_e32 v37, v7
	v_mov_b32_e32 v9, v39
	v_pk_mul_f32 v[26:27], v[36:37], v[8:9]
	v_mov_b32_e32 v42, v46
	v_add_u32_e32 v6, 0x1400, v14
	v_pk_mul_f32 v[30:31], v[26:27], v[42:43]
	v_pk_fma_f32 v[8:9], v[36:37], v[8:9], v[42:43]
	ds_read2_b32 v[50:51], v6 offset0:22 offset1:88
	ds_read2_b32 v[42:43], v4 offset0:186 offset1:252
	ds_read2_b32 v[44:45], v6 offset0:154 offset1:220
	ds_read_b32 v67, v14 offset:10488
	v_mov_b32_e32 v31, v9
	v_mov_b32_e32 v46, v47
	s_waitcnt lgkmcnt(4)
	v_mov_b32_e32 v47, v48
	v_pk_mul_f32 v[60:61], v[30:31], v[46:47]
	v_mov_b32_e32 v52, v40
	s_waitcnt lgkmcnt(3)
	v_mov_b32_e32 v53, v50
	v_pk_mul_f32 v[64:65], v[60:61], v[52:53]
	v_pk_fma_f32 v[52:53], v[30:31], v[46:47], v[52:53]
	v_mov_b32_e32 v40, v41
	v_mov_b32_e32 v65, v53
	v_mov_b32_e32 v41, v49
	v_pk_mul_f32 v[54:55], v[64:65], v[40:41]
	v_mov_b32_e32 v50, v38
	v_pk_mul_f32 v[58:59], v[54:55], v[50:51]
	v_pk_fma_f32 v[40:41], v[64:65], v[40:41], v[50:51]
	v_mov_b32_e32 v38, v39
	v_mov_b32_e32 v59, v41
	s_waitcnt lgkmcnt(2)
	v_mov_b32_e32 v39, v42
	v_pk_mul_f32 v[56:57], v[58:59], v[38:39]
	v_mov_b32_e32 v46, v48
	s_waitcnt lgkmcnt(1)
	v_mov_b32_e32 v47, v44
	v_pk_mul_f32 v[62:63], v[56:57], v[46:47]
	v_pk_fma_f32 v[46:47], v[58:59], v[38:39], v[46:47]
	v_mov_b32_e32 v38, v49
	v_mov_b32_e32 v63, v47
	v_mov_b32_e32 v39, v43
	v_pk_mul_f32 v[48:49], v[62:63], v[38:39]
	v_mov_b32_e32 v44, v42
	v_pk_mul_f32 v[50:51], v[48:49], v[44:45]
	v_pk_fma_f32 v[38:39], v[62:63], v[38:39], v[44:45]
	v_mov_b32_e32 v66, v43
	v_mov_b32_e32 v51, v39
	s_waitcnt lgkmcnt(0)
	v_pk_mul_f32 v[44:45], v[50:51], v[66:67]
	v_mov_b32_e32 v68, v67
	v_mov_b32_e32 v69, v22
	v_pk_mul_f32 v[42:43], v[44:45], v[68:69]
	v_pk_fma_f32 v[66:67], v[50:51], v[66:67], v[68:69]
	v_mul_f32_e32 v34, 0, v23
	v_mov_b32_e32 v43, v67
	ds_write_b64 v1, v[42:43]
	s_waitcnt lgkmcnt(0)
	s_barrier
	v_cmp_lt_i32_e32 vcc, 0, v0
	v_mov_b32_e32 v8, 1.0
	s_and_saveexec_b64 s[4:5], vcc
	s_cbranch_execz .LBB0_397
	v_readlane_b32 s6, v255, 9
	v_mov_b32_e32 v8, 1.0
	v_mov_b32_e32 v77, 0
	v_lshl_add_u32 v1, v3, 3, s6
	s_mov_b64 s[6:7], 0
	v_mov_b32_e32 v4, v0
